# LayerNorm + swa_attn load/wait restructuring, ret_core epilogue and swa_attn next-tile L2 prefetch touches
# baseline (speedup 1.0000x reference)
.LBB0_1391:
	s_lshl_b32 s0, s34, 5
	v_add_u32_e32 v120, s0, v170
	v_mad_i64_i32 v[0:1], s[2:3], v120, s33, v[116:117]
	s_mov_b32 s100, 0x28000
	s_mov_b32 s101, 0
	v_lshl_add_u64 v[200:201], v[0:1], 0, s[100:101]
	global_load_dword v202, v[200:201], off
	global_load_dwordx4 v[92:95], v[0:1], off
	global_load_dwordx4 v[88:91], v[0:1], off offset:32
	global_load_dwordx4 v[84:87], v[0:1], off offset:64
	global_load_dwordx4 v[80:83], v[0:1], off offset:96
	v_or_b32_e32 v0, s0, v122
	s_movk_i32 s31, 0x90
	v_mad_u64_u32 v[8:9], s[2:3], v0, s31, v[100:101]
	v_mov_b32 v64, 0
	v_mov_b32 v65, 0
	v_mov_b32 v66, 0
	v_mov_b32 v67, 0
	v_mov_b32 v68, 0
	v_mov_b32 v69, 0
	v_mov_b32 v70, 0
	v_mov_b32 v71, 0
	v_mov_b32 v72, 0
	v_mov_b32 v73, 0
	v_mov_b32 v74, 0
	v_mov_b32 v75, 0
	v_mov_b32 v76, 0
	v_mov_b32 v77, 0
	v_mov_b32 v78, 0
	v_mov_b32 v79, 0
	ds_read_b128 v[0:3], v8
	ds_read_b128 v[4:7], v8 offset:32
	s_add_i32 s10, s34, 1
	s_lshl_b32 s30, s10, 5
	s_add_i32 s29, s34, 2
	s_lshl_b32 s7, s29, 5
	s_add_i32 s12, s34, 3
	s_add_i32 s13, s34, 4
	s_waitcnt vmcnt(3) lgkmcnt(1)
	v_mfma_f32_32x32x16_f16 v[64:79], v[0:3], v[92:95], v[64:79]
	ds_read_b128 v[0:3], v8 offset:64
	s_waitcnt vmcnt(2) lgkmcnt(1)
	v_mfma_f32_32x32x16_f16 v[64:79], v[4:7], v[88:91], v[64:79]
	s_waitcnt vmcnt(1) lgkmcnt(0)
	v_mfma_f32_32x32x16_f16 v[64:79], v[0:3], v[84:87], v[64:79]
	ds_read_b128 v[0:3], v8 offset:96
	v_mov_b32 v48, 0
	v_mov_b32 v49, 0
	v_mov_b32 v50, 0
	v_mov_b32 v51, 0
	v_mov_b32 v52, 0
	v_mov_b32 v53, 0
	v_mov_b32 v54, 0
	v_mov_b32 v55, 0
	v_mov_b32 v56, 0
	v_mov_b32 v57, 0
	v_mov_b32 v58, 0
	v_mov_b32 v59, 0
	v_mov_b32 v60, 0
	v_mov_b32 v61, 0
	v_mov_b32 v62, 0
	v_mov_b32 v63, 0
	s_waitcnt vmcnt(0) lgkmcnt(0)
	v_mfma_f32_32x32x16_f16 v[64:79], v[0:3], v[80:83], v[64:79]
	v_or_b32_e32 v0, s30, v122
	v_mad_u64_u32 v[8:9], s[2:3], v0, s31, v[100:101]
	ds_read_b128 v[0:3], v8
	ds_read_b128 v[4:7], v8 offset:32
	s_waitcnt lgkmcnt(1)
	v_mfma_f32_32x32x16_f16 v[48:63], v[0:3], v[92:95], v[48:63]
	ds_read_b128 v[0:3], v8 offset:64
	s_waitcnt lgkmcnt(1)
	v_mfma_f32_32x32x16_f16 v[48:63], v[4:7], v[88:91], v[48:63]
	s_waitcnt lgkmcnt(0)
	v_mfma_f32_32x32x16_f16 v[48:63], v[0:3], v[84:87], v[48:63]
	ds_read_b128 v[0:3], v8 offset:96
	v_mov_b32 v32, 0
	v_mov_b32 v33, 0
	v_mov_b32 v34, 0
	v_mov_b32 v35, 0
	v_mov_b32 v36, 0
	v_mov_b32 v37, 0
	v_mov_b32 v38, 0
	v_mov_b32 v39, 0
	v_mov_b32 v40, 0
	v_mov_b32 v41, 0
	v_mov_b32 v42, 0
	v_mov_b32 v43, 0
	v_mov_b32 v44, 0
	v_mov_b32 v45, 0
	v_mov_b32 v46, 0
	v_mov_b32 v47, 0
	s_waitcnt lgkmcnt(0)
	v_mfma_f32_32x32x16_f16 v[48:63], v[0:3], v[80:83], v[48:63]
	v_or_b32_e32 v0, s7, v122
	v_mad_u64_u32 v[8:9], s[2:3], v0, s31, v[100:101]
	ds_read_b128 v[0:3], v8
	ds_read_b128 v[4:7], v8 offset:32
	s_lshl_b32 s3, s12, 5
	s_lshl_b32 s2, s13, 5
	v_or_b32_e32 v121, s2, v122
	s_waitcnt lgkmcnt(1)
	v_mfma_f32_32x32x16_f16 v[32:47], v[0:3], v[92:95], v[32:47]
	ds_read_b128 v[0:3], v8 offset:64
	v_mad_u64_u32 v[180:181], s[8:9], v121, s31, v[100:101]
	s_waitcnt lgkmcnt(1)
	v_mfma_f32_32x32x16_f16 v[32:47], v[4:7], v[88:91], v[32:47]
	s_waitcnt lgkmcnt(0)
	v_mfma_f32_32x32x16_f16 v[32:47], v[0:3], v[84:87], v[32:47]
	ds_read_b128 v[0:3], v8 offset:96
	v_mov_b32 v16, 0
	v_mov_b32 v17, 0
	v_mov_b32 v18, 0
	v_mov_b32 v19, 0
	v_mov_b32 v20, 0
	v_mov_b32 v21, 0
	v_mov_b32 v22, 0
	v_mov_b32 v23, 0
	v_mov_b32 v24, 0
	v_mov_b32 v25, 0
	v_mov_b32 v26, 0
	v_mov_b32 v27, 0
	v_mov_b32 v28, 0
	v_mov_b32 v29, 0
	v_mov_b32 v30, 0
	v_mov_b32 v31, 0
	s_waitcnt lgkmcnt(0)
	v_mfma_f32_32x32x16_f16 v[32:47], v[0:3], v[80:83], v[32:47]
	v_or_b32_e32 v0, s3, v122
	v_mad_u64_u32 v[8:9], s[8:9], v0, s31, v[100:101]
	ds_read_b128 v[0:3], v8
	ds_read_b128 v[4:7], v8 offset:32
	s_waitcnt lgkmcnt(1)
	v_mfma_f32_32x32x16_f16 v[16:31], v[0:3], v[92:95], v[16:31]
	ds_read_b128 v[0:3], v8 offset:64
	s_waitcnt lgkmcnt(1)
	v_mfma_f32_32x32x16_f16 v[16:31], v[4:7], v[88:91], v[16:31]
	s_waitcnt lgkmcnt(0)
	v_mfma_f32_32x32x16_f16 v[16:31], v[0:3], v[84:87], v[16:31]
	ds_read_b128 v[0:3], v8 offset:96
	s_waitcnt lgkmcnt(0)
	v_mfma_f32_32x32x16_f16 v[16:31], v[0:3], v[80:83], v[16:31]
	v_mov_b32 v0, 0
	v_mov_b32 v1, 0
	v_mov_b32 v2, 0
	v_mov_b32 v3, 0
	v_mov_b32 v4, 0
	v_mov_b32 v5, 0
	v_mov_b32 v6, 0
	v_mov_b32 v7, 0
	v_mov_b32 v8, 0
	v_mov_b32 v9, 0
	v_mov_b32 v10, 0
	v_mov_b32 v11, 0
	v_mov_b32 v12, 0
	v_mov_b32 v13, 0
	v_mov_b32 v14, 0
	v_mov_b32 v15, 0
	ds_read_b128 v[172:175], v180
	ds_read_b128 v[176:179], v180 offset:32
	s_waitcnt lgkmcnt(1)
	v_mfma_f32_32x32x16_f16 v[0:15], v[172:175], v[92:95], v[0:15]
	s_waitcnt lgkmcnt(0)
	v_mfma_f32_32x32x16_f16 v[0:15], v[176:179], v[88:91], v[0:15]
	ds_read_b128 v[88:91], v180 offset:64
	s_waitcnt lgkmcnt(0)
	v_mfma_f32_32x32x16_f16 v[0:15], v[88:91], v[84:87], v[0:15]
	ds_read_b128 v[84:87], v180 offset:96
	s_waitcnt lgkmcnt(0)
	v_mfma_f32_32x32x16_f16 v[0:15], v[84:87], v[80:83], v[0:15]
	v_add_u32_e32 v85, s0, v102
	v_cmp_lt_i32_e32 vcc, s90, v85
	s_or_b64 s[8:9], s[22:23], vcc
	s_and_b64 s[36:37], s[40:41], s[8:9]
	v_mov_b32_e32 v80, 0xf149f2ca
	v_mov_b32_e32 v81, 0xf149f2ca
	s_and_saveexec_b64 s[8:9], s[36:37]
	s_cbranch_execz .LBB0_1393
	ds_read_b32 v81, v128 offset:512
	s_waitcnt lgkmcnt(0)
	v_add_f32_e32 v81, v64, v81
